# adds: FoX decay-table fill loop issues two iterations' loads before waiting (one global round trip instead of two per unit)
# speedup vs baseline: 1.0135x; 1.0014x over previous
.LBB0_343:
	s_mov_b64 s[6:7], exec
	global_load_dwordx2 v[18:19], v[10:11], off
	v_add_u32_e32 v8, 0x200, v8
	v_cmp_gt_i32_e32 vcc, s16, v8
	v_lshl_add_u64 v[10:11], v[10:11], 0, s[20:21]
	s_and_b64 s[100:101], s[6:7], vcc
	s_mov_b64 exec, s[100:101]
	s_cbranch_execz .Lfox_ck_noB
	global_load_dwordx2 v[184:185], v[10:11], off
	v_add_u32_e32 v8, 0x200, v8
	v_lshl_add_u64 v[10:11], v[10:11], 0, s[20:21]
.Lfox_ck_noB:
	s_mov_b64 exec, s[6:7]
	s_waitcnt vmcnt(0)
	v_add_f64 v[18:19], v[18:19], -v[4:5]
	v_mul_f64 v[18:19], v[18:19], s[18:19]
	v_cvt_f32_f64_e32 v9, v[18:19]
	ds_write_b32 v16, v9
	s_mov_b64 exec, s[100:101]
	s_cbranch_execz .LBB0_344
	v_add_f64 v[184:185], v[184:185], -v[4:5]
	v_mul_f64 v[184:185], v[184:185], s[18:19]
	v_cvt_f32_f64_e32 v9, v[184:185]
	ds_write_b32 v16, v9 offset:2048
	v_add_u32_e32 v16, 0x1000, v16
	v_cmp_gt_i32_e32 vcc, s16, v8
	s_nop 0
	s_and_b64 exec, exec, vcc
	s_cbranch_execnz .LBB0_343

	.amdhsa_kernel _Z8yoco_fwd4Args
		.amdhsa_group_segment_fixed_size 0
		.amdhsa_private_segment_fixed_size 0
		.amdhsa_kernarg_size 416
		.amdhsa_user_sgpr_count 2
		.amdhsa_user_sgpr_dispatch_ptr 0
		.amdhsa_user_sgpr_queue_ptr 0
		.amdhsa_user_sgpr_kernarg_segment_ptr 1
		.amdhsa_user_sgpr_dispatch_id 0
		.amdhsa_user_sgpr_kernarg_preload_length 0
		.amdhsa_user_sgpr_kernarg_preload_offset 0
		.amdhsa_user_sgpr_private_segment_size 0
		.amdhsa_uses_dynamic_stack 0
		.amdhsa_enable_private_segment 0
		.amdhsa_system_sgpr_workgroup_id_x 1
		.amdhsa_system_sgpr_workgroup_id_y 0
		.amdhsa_system_sgpr_workgroup_id_z 0
		.amdhsa_system_sgpr_workgroup_info 0
		.amdhsa_system_vgpr_workitem_id 2
		.amdhsa_next_free_vgpr 254
		.amdhsa_next_free_sgpr 102
		.amdhsa_accum_offset 256
		.amdhsa_reserve_vcc 1
		.amdhsa_float_round_mode_32 0
		.amdhsa_float_round_mode_16_64 0
		.amdhsa_float_denorm_mode_32 3
		.amdhsa_float_denorm_mode_16_64 3
		.amdhsa_dx10_clamp 1
		.amdhsa_ieee_mode 1
		.amdhsa_fp16_overflow 0
		.amdhsa_tg_split 0
		.amdhsa_exception_fp_ieee_invalid_op 0
		.amdhsa_exception_fp_denorm_src 0
		.amdhsa_exception_fp_ieee_div_zero 0
		.amdhsa_exception_fp_ieee_overflow 0
		.amdhsa_exception_fp_ieee_underflow 0
		.amdhsa_exception_fp_ieee_inexact 0
		.amdhsa_exception_int_div_zero 0
	.end_amdhsa_kernel

amdhsa.kernels:
  - .agpr_count:     0
    .args:
      - .offset:         0
        .size:           160
        .value_kind:     by_value
      - .offset:         160
        .size:           4
        .value_kind:     hidden_block_count_x
      - .offset:         164
        .size:           4
        .value_kind:     hidden_block_count_y
      - .offset:         168
        .size:           4
        .value_kind:     hidden_block_count_z
      - .offset:         172
        .size:           2
        .value_kind:     hidden_group_size_x
      - .offset:         174
        .size:           2
        .value_kind:     hidden_group_size_y
      - .offset:         176
        .size:           2
        .value_kind:     hidden_group_size_z
      - .offset:         178
        .size:           2
        .value_kind:     hidden_remainder_x
      - .offset:         180
        .size:           2
        .value_kind:     hidden_remainder_y
      - .offset:         182
        .size:           2
        .value_kind:     hidden_remainder_z
      - .offset:         200
        .size:           8
        .value_kind:     hidden_global_offset_x
      - .offset:         208
        .size:           8
        .value_kind:     hidden_global_offset_y
      - .offset:         216
        .size:           8
        .value_kind:     hidden_global_offset_z
      - .offset:         224
        .size:           2
        .value_kind:     hidden_grid_dims
      - .offset:         248
        .size:           8
        .value_kind:     hidden_multigrid_sync_arg
      - .offset:         280
        .size:           4
        .value_kind:     hidden_dynamic_lds_size
    .group_segment_fixed_size: 0
    .kernarg_segment_align: 8
    .kernarg_segment_size: 416
    .language:       OpenCL C
    .language_version:
      - 2
      - 0
    .max_flat_workgroup_size: 512
    .name:           _Z8yoco_fwd4Args
    .private_segment_fixed_size: 0
    .sgpr_count:     108
    .sgpr_spill_count: 19
    .symbol:         _Z8yoco_fwd4Args.kd
    .uniform_work_group_size: 1
    .uses_dynamic_stack: false
    .vgpr_count:     254
    .vgpr_spill_count: 0
    .wavefront_size: 64
